# p4wide_v110 + hg_prep state-delta stores widened (v_permlane16_swap pairs -> dwordx4, 14 of 16 stores)
# baseline (speedup 1.0000x reference)
.LBB0_872:
	s_or_b64 exec, exec, s[0:1]
	v_mad_u32_u24 v56, v67, s35, v60
	s_waitcnt lgkmcnt(0)
	s_barrier
	ds_read_b128 v[70:73], v56
	v_lshl_or_b32 v54, v53, 5, v67
	v_mad_u64_u32 v[54:55], s[0:1], v54, s35, v[60:61]
	ds_read_b128 v[60:63], v54 offset:35840
	ds_read_b128 v[74:77], v54 offset:35904
	ds_read_b128 v[78:81], v56 offset:64
	ds_read_b128 v[86:89], v56 offset:2304
	ds_read_b128 v[90:93], v56 offset:2368
	ds_read_b128 v[98:101], v56 offset:4608
	ds_read_b128 v[102:105], v56 offset:4672
	s_waitcnt lgkmcnt(6)
	v_mfma_f32_16x16x32_bf16 v[82:85], v[70:73], v[60:63], 0
	ds_read_b128 v[110:113], v56 offset:6912
	ds_read_b128 v[114:117], v56 offset:6976
	v_lshlrev_b32_e32 v55, 7, v67
	v_lshlrev_b64 v[26:27], 13, v[58:59]
	s_waitcnt lgkmcnt(5)
	v_mfma_f32_16x16x32_bf16 v[94:97], v[86:89], v[60:63], 0
	v_lshlrev_b64 v[58:59], 15, v[58:59]
	v_lshl_or_b32 v166, v53, 12, v55
	ds_read_b128 v[122:125], v56 offset:9216
	ds_read_b128 v[126:129], v56 offset:9280
	s_waitcnt lgkmcnt(5)
	v_mfma_f32_16x16x32_bf16 v[106:109], v[98:101], v[60:63], 0
	ds_read_b128 v[134:137], v56 offset:11520
	ds_read_b128 v[138:141], v56 offset:11584
	v_lshl_add_u64 v[58:59], s[8:9], 0, v[58:59]
	v_ashrrev_i32_e32 v167, 31, v166
	s_waitcnt lgkmcnt(5)
	v_mfma_f32_16x16x32_bf16 v[118:121], v[110:113], v[60:63], 0
	ds_read_b128 v[146:149], v56 offset:13824
	ds_read_b128 v[150:153], v56 offset:13888
	ds_read_b128 v[158:161], v56 offset:16128
	ds_read_b128 v[162:165], v56 offset:16192
	v_lshl_add_u64 v[166:167], v[166:167], 1, v[58:59]
	v_mfma_f32_16x16x32_bf16 v[82:85], v[78:81], v[74:77], v[82:85]
	v_lshlrev_b32_e32 v168, 1, v68
	v_mov_b32_e32 v169, v24
	v_lshl_add_u64 v[170:171], v[166:167], 0, v[168:169]
	v_bfe_u32 v178, v181, 4, 1
	v_mul_u32_u24_e32 v178, 24, v178
	v_mov_b32_e32 v179, 0
	v_lshl_add_u64 v[176:177], v[170:171], 0, v[178:179]
	v_mfma_f32_16x16x32_bf16 v[94:97], v[90:93], v[74:77], v[94:97]
	v_lshlrev_b32_e32 v52, 2, v52
	s_nop 2
	v_cvt_pk_bf16_f32 v58, v82, v83
	v_cvt_pk_bf16_f32 v59, v84, v85
	v_mfma_f32_16x16x32_bf16 v[106:109], v[102:105], v[74:77], v[106:109]
	v_mov_b32_e32 v172, v58
	v_mov_b32_e32 v173, v59
	v_cvt_pk_bf16_f32 v58, v94, v95
	v_cvt_pk_bf16_f32 v59, v96, v97
	s_waitcnt lgkmcnt(8)
	v_mfma_f32_16x16x32_bf16 v[82:85], v[114:117], v[74:77], v[118:121]
	v_mov_b32_e32 v174, v58
	v_mov_b32_e32 v175, v59
	s_nop 1
	v_permlane16_swap_b32_e32 v172, v174
	v_permlane16_swap_b32_e32 v173, v175
	global_store_dwordx4 v[176:177], v[172:175], off
	s_nop 1
	v_cvt_pk_bf16_f32 v58, v106, v107
	v_cvt_pk_bf16_f32 v59, v108, v109
	s_waitcnt lgkmcnt(5)
	v_mfma_f32_16x16x32_bf16 v[142:145], v[134:137], v[60:63], 0
	v_mov_b32_e32 v172, v58
	v_mov_b32_e32 v173, v59
	v_cvt_pk_bf16_f32 v58, v82, v83
	v_cvt_pk_bf16_f32 v59, v84, v85
	v_mfma_f32_16x16x32_bf16 v[130:133], v[122:125], v[60:63], 0
	ds_read_b128 v[82:85], v54 offset:38144
	v_mov_b32_e32 v174, v58
	v_mov_b32_e32 v175, v59
	s_nop 1
	v_permlane16_swap_b32_e32 v172, v174
	v_permlane16_swap_b32_e32 v173, v175
	global_store_dwordx4 v[176:177], v[172:175], off offset:64
	v_and_b32_e32 v52, 0xfc, v52
	s_waitcnt lgkmcnt(4)
	v_mfma_f32_16x16x32_bf16 v[154:157], v[146:149], v[60:63], 0
	v_lshl_add_u64 v[26:27], v[26:27], 1, s[10:11]
	s_and_b64 vcc, exec, s[12:13]
	s_mov_b32 s14, s39
	s_waitcnt lgkmcnt(2)
	v_mfma_f32_16x16x32_bf16 v[60:63], v[158:161], v[60:63], 0
	v_mfma_f32_16x16x32_bf16 v[94:97], v[138:141], v[74:77], v[142:145]
	v_mfma_f32_16x16x32_bf16 v[118:121], v[126:129], v[74:77], v[130:133]
	v_mfma_f32_16x16x32_bf16 v[106:109], v[150:153], v[74:77], v[154:157]
	s_nop 5
	v_cvt_pk_bf16_f32 v55, v96, v97
	s_waitcnt lgkmcnt(1)
	v_mfma_f32_16x16x32_bf16 v[58:61], v[162:165], v[74:77], v[60:63]
	ds_read_b128 v[74:77], v54 offset:38208
	v_cvt_pk_bf16_f32 v54, v94, v95
	global_store_dwordx2 v[170:171], v[54:55], off offset:160
	s_waitcnt lgkmcnt(1)
	v_mfma_f32_16x16x32_bf16 v[68:71], v[70:73], v[82:85], 0
	v_cvt_pk_bf16_f32 v54, v106, v107
	v_cvt_pk_bf16_f32 v55, v108, v109
	v_mov_b32_e32 v172, v54
	v_mov_b32_e32 v173, v55
	v_cvt_pk_bf16_f32 v54, v58, v59
	v_cvt_pk_bf16_f32 v55, v60, v61
	s_waitcnt lgkmcnt(0)
	v_mfma_f32_16x16x32_bf16 v[58:61], v[78:81], v[74:77], v[68:71]
	v_mov_b32_e32 v174, v54
	v_mov_b32_e32 v175, v55
	s_nop 1
	v_permlane16_swap_b32_e32 v172, v174
	v_permlane16_swap_b32_e32 v173, v175
	global_store_dwordx4 v[176:177], v[172:175], off offset:192
	v_lshl_add_u64 v[54:55], v[166:167], 0, s[4:5]
	v_cvt_pk_bf16_f32 v62, v118, v119
	v_mfma_f32_16x16x32_bf16 v[86:89], v[86:89], v[82:85], 0
	v_cvt_pk_bf16_f32 v63, v120, v121
	s_nop 2
	v_cvt_pk_bf16_f32 v58, v58, v59
	v_cvt_pk_bf16_f32 v59, v60, v61
	v_lshl_add_u64 v[60:61], v[54:55], 0, v[168:169]
	v_lshl_add_u64 v[176:177], v[60:61], 0, v[178:179]
	v_mfma_f32_16x16x32_bf16 v[94:97], v[98:101], v[82:85], 0
	v_mov_b32_e32 v172, v58
	v_mov_b32_e32 v173, v59
	global_store_dwordx2 v[170:171], v[62:63], off offset:128
	v_or_b32_e32 v72, 32, v168
	v_mfma_f32_16x16x32_bf16 v[58:61], v[90:93], v[74:77], v[86:89]
	v_mov_b32_e32 v73, v24
	v_lshl_add_u64 v[72:73], v[54:55], 0, v[72:73]
	v_mfma_f32_16x16x32_bf16 v[68:71], v[110:113], v[82:85], 0
	v_mfma_f32_16x16x32_bf16 v[78:81], v[102:105], v[74:77], v[94:97]
	s_nop 3
	v_cvt_pk_bf16_f32 v62, v58, v59
	v_cvt_pk_bf16_f32 v63, v60, v61
	v_mov_b32_e32 v174, v62
	v_mov_b32_e32 v175, v63
	s_nop 1
	v_permlane16_swap_b32_e32 v172, v174
	v_permlane16_swap_b32_e32 v173, v175
	global_store_dwordx4 v[176:177], v[172:175], off
	v_mfma_f32_16x16x32_bf16 v[58:61], v[122:125], v[82:85], 0
	v_or_b32_e32 v72, 64, v168
	v_mov_b32_e32 v73, v24
	v_cvt_pk_bf16_f32 v62, v78, v79
	v_mfma_f32_16x16x32_bf16 v[68:71], v[114:117], v[74:77], v[68:71]
	v_cvt_pk_bf16_f32 v63, v80, v81
	v_lshl_add_u64 v[72:73], v[54:55], 0, v[72:73]
	v_mov_b32_e32 v172, v62
	v_mov_b32_e32 v173, v63
	v_mfma_f32_16x16x32_bf16 v[58:61], v[126:129], v[74:77], v[58:61]
	v_or_b32_e32 v72, 0x60, v168
	v_mov_b32_e32 v73, v24
	s_nop 1
	v_cvt_pk_bf16_f32 v62, v68, v69
	v_cvt_pk_bf16_f32 v63, v70, v71
	v_lshl_add_u64 v[72:73], v[54:55], 0, v[72:73]
	v_mov_b32_e32 v174, v62
	v_mov_b32_e32 v175, v63
	s_nop 1
	v_permlane16_swap_b32_e32 v172, v174
	v_permlane16_swap_b32_e32 v173, v175
	global_store_dwordx4 v[176:177], v[172:175], off offset:64
	v_or_b32_e32 v72, 0x80, v168
	v_mov_b32_e32 v73, v24
	v_cvt_pk_bf16_f32 v62, v58, v59
	v_cvt_pk_bf16_f32 v63, v60, v61
	v_lshl_add_u64 v[72:73], v[54:55], 0, v[72:73]
	v_mfma_f32_16x16x32_bf16 v[78:81], v[134:137], v[82:85], 0
	v_mov_b32_e32 v172, v62
	v_mov_b32_e32 v173, v63
	v_mul_lo_u32 v62, v65, s35
	v_or_b32_e32 v102, 0xa0, v168
	v_mfma_f32_16x16x32_bf16 v[68:71], v[146:149], v[82:85], 0
	v_mov_b32_e32 v103, v24
	v_lshl_add_u64 v[112:113], v[54:55], 0, v[102:103]
	v_or_b32_e32 v136, 0xc0, v168
	v_mfma_f32_16x16x32_bf16 v[58:61], v[158:161], v[82:85], 0
	v_lshl_add_u32 v82, v66, 1, v62
	ds_read_b128 v[62:65], v82 offset:54272
	v_mov_b32_e32 v137, v24
	v_mfma_f32_16x16x32_bf16 v[78:81], v[138:141], v[74:77], v[78:81]
	v_mfma_f32_16x16x32_bf16 v[66:69], v[150:153], v[74:77], v[68:71]
	s_nop 2
	ds_read_b128 v[70:73], v56 offset:35840
	s_nop 2
	v_cvt_pk_bf16_f32 v110, v78, v79
	v_cvt_pk_bf16_f32 v111, v80, v81
	v_mfma_f32_16x16x32_bf16 v[58:61], v[162:165], v[74:77], v[58:61]
	ds_read_b128 v[74:77], v56 offset:38144
	ds_read_b128 v[78:81], v82 offset:54336
	ds_read_b128 v[82:85], v56 offset:35904
	ds_read_b128 v[86:89], v56 offset:40448
	ds_read_b128 v[90:93], v56 offset:38208
	ds_read_b128 v[94:97], v56 offset:42752
	ds_read_b128 v[98:101], v56 offset:40512
	ds_read_b128 v[102:105], v56 offset:45056
	ds_read_b128 v[106:109], v56 offset:42816
	v_mov_b32_e32 v174, v110
	v_mov_b32_e32 v175, v111
	s_nop 1
	v_permlane16_swap_b32_e32 v172, v174
	v_permlane16_swap_b32_e32 v173, v175
	global_store_dwordx4 v[176:177], v[172:175], off offset:128
	ds_read_b128 v[110:113], v56 offset:47360
	ds_read_b128 v[114:117], v56 offset:45120
	v_cvt_pk_bf16_f32 v134, v66, v67
	ds_read_b128 v[118:121], v56 offset:49664
	ds_read_b128 v[122:125], v56 offset:47424
	v_cvt_pk_bf16_f32 v135, v68, v69
	ds_read_b128 v[66:69], v56 offset:51968
	ds_read_b128 v[126:129], v56 offset:49728
	s_waitcnt lgkmcnt(14)
	v_mfma_f32_16x16x32_bf16 v[70:73], v[70:73], v[62:65], 0
	ds_read_b128 v[130:133], v56 offset:52032
	v_mfma_f32_16x16x32_bf16 v[74:77], v[74:77], v[62:65], 0
	s_waitcnt lgkmcnt(12)
	v_mfma_f32_16x16x32_bf16 v[86:89], v[86:89], v[62:65], 0
	s_waitcnt lgkmcnt(10)
	v_mfma_f32_16x16x32_bf16 v[94:97], v[94:97], v[62:65], 0
	s_waitcnt lgkmcnt(8)
	v_mfma_f32_16x16x32_bf16 v[102:105], v[102:105], v[62:65], 0
	s_waitcnt lgkmcnt(6)
	v_mfma_f32_16x16x32_bf16 v[110:113], v[110:113], v[62:65], 0
	s_waitcnt lgkmcnt(4)
	v_mfma_f32_16x16x32_bf16 v[118:121], v[118:121], v[62:65], 0
	s_waitcnt lgkmcnt(2)
	v_mfma_f32_16x16x32_bf16 v[62:65], v[66:69], v[62:65], 0
	v_lshl_add_u64 v[66:67], v[54:55], 0, v[136:137]
	v_mov_b32_e32 v172, v134
	v_mov_b32_e32 v173, v135
	v_cvt_pk_bf16_f32 v134, v58, v59
	v_mfma_f32_16x16x32_bf16 v[66:69], v[82:85], v[78:81], v[70:73]
	v_cvt_pk_bf16_f32 v135, v60, v61
	v_mfma_f32_16x16x32_bf16 v[58:61], v[90:93], v[78:81], v[74:77]
	s_nop 0
	v_or_b32_e32 v70, 0xe0, v168
	v_mov_b32_e32 v71, v24
	v_lshl_add_u64 v[54:55], v[54:55], 0, v[70:71]
	v_lshl_or_b32 v76, v53, 11, v52
	v_ashrrev_i32_e32 v77, 31, v76
	v_mov_b32_e32 v174, v134
	v_mov_b32_e32 v175, v135
	s_nop 1
	v_permlane16_swap_b32_e32 v172, v174
	v_permlane16_swap_b32_e32 v173, v175
	global_store_dwordx4 v[176:177], v[172:175], off offset:192
	v_cvt_pk_bf16_f32 v74, v66, v67
	v_cvt_pk_bf16_f32 v75, v68, v69
	v_mfma_f32_16x16x32_bf16 v[52:55], v[114:117], v[78:81], v[102:105]
	v_lshl_add_u64 v[26:27], v[76:77], 1, v[26:27]
	global_store_dwordx2 v[26:27], v[74:75], off
	v_cvt_pk_bf16_f32 v58, v58, v59
	v_mfma_f32_16x16x32_bf16 v[74:77], v[122:125], v[78:81], v[110:113]
	v_cvt_pk_bf16_f32 v59, v60, v61
	global_store_dwordx2 v[26:27], v[58:59], off offset:512
	s_nop 1
	v_cvt_pk_bf16_f32 v52, v52, v53
	s_waitcnt lgkmcnt(1)
	v_mfma_f32_16x16x32_bf16 v[58:61], v[126:129], v[78:81], v[118:121]
	v_cvt_pk_bf16_f32 v53, v54, v55
	global_store_dwordx2 v[26:27], v[52:53], off offset:2048
	v_cvt_pk_bf16_f32 v52, v74, v75
	s_waitcnt lgkmcnt(0)
	v_mfma_f32_16x16x32_bf16 v[62:65], v[130:133], v[78:81], v[62:65]
	v_cvt_pk_bf16_f32 v53, v76, v77
	global_store_dwordx2 v[26:27], v[52:53], off offset:2560
	s_nop 0
	v_cvt_pk_bf16_f32 v52, v58, v59
	v_mfma_f32_16x16x32_bf16 v[70:73], v[98:101], v[78:81], v[86:89]
	v_cvt_pk_bf16_f32 v53, v60, v61
	global_store_dwordx2 v[26:27], v[52:53], off offset:3072
	s_nop 0
	v_cvt_pk_bf16_f32 v52, v62, v63
	v_mfma_f32_16x16x32_bf16 v[66:69], v[106:109], v[78:81], v[94:97]
	v_cvt_pk_bf16_f32 v53, v64, v65
	s_nop 1
	v_cvt_pk_bf16_f32 v70, v70, v71
	v_cvt_pk_bf16_f32 v71, v72, v73
	global_store_dwordx2 v[26:27], v[52:53], off offset:3584
	s_waitcnt vmcnt(26)
	v_mov_b32_e32 v53, v25
	v_cvt_pk_bf16_f32 v66, v66, v67
	v_cvt_pk_bf16_f32 v67, v68, v69
	v_mov_b32_e32 v60, v57
	global_store_dwordx2 v[26:27], v[70:71], off offset:1024
	global_store_dwordx2 v[26:27], v[66:67], off offset:1536
	s_cbranch_vccnz .LBB0_904
